# slot-side transposed bf16 weight stores (w_out_a/w_in_b/w_out_b bodies) marked nt
# baseline (speedup 1.0000x reference)
; #define LAS __attribute__((address_space(3)))
; DI unsigned pk2(float a, float b) { f32x2 v = {a, b}; bf16v2 r = __builtin_convertvector(v, bf16v2); return __builtin_bit_cast(unsigned, r); }
; DI void p0_transpose_item(const float* W, int K, int N, bf16_t* WT, LAS float* scr, int item, int lane) {
;     ...
;     for (int i = 0; i < 16; ++i) v[i] = *(const f32x4*)(W + (size_t)(k0 + kr + 8 * i) * N + n0 + 4 * n4);
; #pragma unroll
;     for (int i = 0; i < 16; ++i) { LAS float* d = scr + (kr + 8 * i) * 33 + 4 * n4; d[0] = v[i][0]; d[1] = v[i][1]; d[2] = v[i][2]; d[3] = v[i][3]; }
;     asm volatile("s_waitcnt lgkmcnt(0)" ::: "memory");
;     const int c = lane & 15;
; #pragma unroll
;     for (int j = 0; j < 8; ++j) { const int n = (lane >> 4) + 4 * j; const LAS float* s = scr + (8 * c) * 33 + n;
;         u32x4 o; o.x = pk2(s[0 * 33], s[1 * 33]); o.y = pk2(s[2 * 33], s[3 * 33]); o.z = pk2(s[4 * 33], s[5 * 33]); o.w = pk2(s[6 * 33], s[7 * 33]);
;         *(u32x4*)(WT + (size_t)(n0 + n) * K + k0 + 8 * c) = o; }
; DI void phase_p0(const Params& p, LAS unsigned char* lds, int gw, int NGW, int wave, int lane) {
;     ...
;         { const int j = r / I_OUT; p0_transpose_item(p.w_out_b + (size_t)j * D * D, D, D, (bf16_t*)(p.ws + WS_W + j * WPAIR + WO_OUTB), scr, r % I_OUT, lane); }
.LBB0_17:
	s_cmpk_gt_i32 s64, 0x11ff
	s_mov_b64 s[16:17], -1
	s_cbranch_scc0 .LBB0_27
	s_cmpk_gt_u32 s64, 0x19ff
	s_cbranch_scc0 .LBB0_24
	s_cmpk_gt_u32 s64, 0x39ff
	s_cbranch_scc0 .LBB0_21
	s_add_i32 s8, s64, 0xffffc600
	s_lshr_b32 s8, s8, 10
	s_lshl_b64 s[16:17], s[8:9], 24
	s_waitcnt lgkmcnt(0)
	s_add_u32 s16, s86, s16
	s_addc_u32 s17, s87, s17
	s_mul_hi_u32 s18, s8, 0x4200000
	s_mul_i32 s8, s8, 0x4200000
	s_add_u32 s19, s94, s8
	s_addc_u32 s18, s95, s18
	s_and_b32 s8, s20, 0x7e0
	s_and_b32 s65, s1, 0x780
	s_lshl_b32 s66, s8, 2
	s_add_u32 s16, s16, s66
	v_or_b32_e32 v5, s65, v6
	s_addc_u32 s17, s17, 0
	v_lshl_add_u64 v[50:51], s[16:17], 0, v[2:3]
	v_lshlrev_b32_e32 v52, 13, v5
	v_mov_b32_e32 v53, v3
	v_lshl_add_u64 v[110:111], v[50:51], 0, v[52:53]
	v_add_co_u32_e32 v54, vcc, s22, v110
	s_lshl_b32 s16, s65, 1
	s_nop 0
	v_addc_co_u32_e32 v55, vcc, 0, v111, vcc
	v_add_co_u32_e32 v58, vcc, s23, v110
	global_load_dwordx4 v[50:53], v[110:111], off nt
	s_nop 0
	global_load_dwordx4 v[54:57], v[54:55], off nt
	v_addc_co_u32_e32 v59, vcc, 0, v111, vcc
	v_add_co_u32_e32 v62, vcc, s24, v110
	s_add_u32 s16, s19, s16
	s_nop 0
	v_addc_co_u32_e32 v63, vcc, 0, v111, vcc
	v_add_co_u32_e32 v66, vcc, s25, v110
	global_load_dwordx4 v[58:61], v[58:59], off nt
	s_nop 0
	global_load_dwordx4 v[62:65], v[62:63], off nt
	v_addc_co_u32_e32 v67, vcc, 0, v111, vcc
	v_add_co_u32_e32 v70, vcc, s26, v110
	s_addc_u32 s17, s18, 0
	s_nop 0
	v_addc_co_u32_e32 v71, vcc, 0, v111, vcc
	v_add_co_u32_e32 v74, vcc, s27, v110
	global_load_dwordx4 v[66:69], v[66:67], off nt
	s_nop 0
	global_load_dwordx4 v[70:73], v[70:71], off nt
	v_addc_co_u32_e32 v75, vcc, 0, v111, vcc
	v_add_co_u32_e32 v78, vcc, s28, v110
	v_mov_b32_e32 v5, v3
	s_nop 0
	v_addc_co_u32_e32 v79, vcc, 0, v111, vcc
	v_add_co_u32_e32 v82, vcc, s29, v110
	global_load_dwordx4 v[74:77], v[74:75], off nt
	s_nop 0
	global_load_dwordx4 v[78:81], v[78:79], off nt
	v_addc_co_u32_e32 v83, vcc, 0, v111, vcc
	v_add_co_u32_e32 v86, vcc, s30, v110
	s_nop 1
	v_addc_co_u32_e32 v87, vcc, 0, v111, vcc
	v_add_co_u32_e32 v90, vcc, s31, v110
	global_load_dwordx4 v[82:85], v[82:83], off nt
	s_nop 0
	global_load_dwordx4 v[86:89], v[86:87], off nt
	v_addc_co_u32_e32 v91, vcc, 0, v111, vcc
	v_add_co_u32_e32 v94, vcc, s33, v110
	s_nop 1
	v_addc_co_u32_e32 v95, vcc, 0, v111, vcc
	v_add_co_u32_e32 v98, vcc, s34, v110
	global_load_dwordx4 v[90:93], v[90:91], off nt
	s_nop 0
	global_load_dwordx4 v[94:97], v[94:95], off nt
	v_addc_co_u32_e32 v99, vcc, 0, v111, vcc
	v_add_co_u32_e32 v102, vcc, s35, v110
	s_nop 1
	v_addc_co_u32_e32 v103, vcc, 0, v111, vcc
	global_load_dwordx4 v[98:101], v[98:99], off nt
	s_nop 0
	global_load_dwordx4 v[102:105], v[102:103], off nt
	v_add_co_u32_e32 v106, vcc, s36, v110
	s_nop 1
	v_addc_co_u32_e32 v107, vcc, 0, v111, vcc
	global_load_dwordx4 v[106:109], v[106:107], off nt
	v_add_co_u32_e32 v110, vcc, s37, v110
	s_nop 1
	v_addc_co_u32_e32 v111, vcc, 0, v111, vcc
	global_load_dwordx4 v[110:113], v[110:111], off nt
	s_waitcnt vmcnt(15)
	ds_write2_b32 v7, v50, v51 offset1:1
	ds_write2_b32 v7, v52, v53 offset0:2 offset1:3
	s_waitcnt vmcnt(14)
	ds_write2_b32 v17, v54, v55 offset1:1
	ds_write2_b32 v18, v56, v57 offset1:1
	s_waitcnt vmcnt(13)
	ds_write2_b32 v19, v58, v59 offset1:1
	ds_write2_b32 v20, v60, v61 offset1:1
	s_waitcnt vmcnt(12)
	ds_write2_b32 v21, v62, v63 offset1:1
	ds_write2_b32 v22, v64, v65 offset1:1
	s_waitcnt vmcnt(11)
	ds_write2_b32 v23, v66, v67 offset1:1
	ds_write2_b32 v24, v68, v69 offset1:1
	s_waitcnt vmcnt(10)
	ds_write2_b32 v25, v70, v71 offset1:1
	ds_write2_b32 v26, v72, v73 offset1:1
	s_waitcnt vmcnt(9)
	ds_write2_b32 v27, v74, v75 offset1:1
	ds_write2_b32 v28, v76, v77 offset1:1
	s_waitcnt vmcnt(8)
	ds_write2_b32 v29, v78, v79 offset1:1
	ds_write2_b32 v30, v80, v81 offset1:1
	s_waitcnt vmcnt(7)
	ds_write2_b32 v31, v82, v83 offset1:1
	ds_write2_b32 v32, v84, v85 offset1:1
	s_waitcnt vmcnt(6)
	ds_write2_b32 v33, v86, v87 offset1:1
	ds_write2_b32 v35, v88, v89 offset1:1
	s_waitcnt vmcnt(5)
	ds_write2_b32 v36, v90, v91 offset1:1
	ds_write2_b32 v37, v92, v93 offset1:1
	s_waitcnt vmcnt(4)
	ds_write2_b32 v38, v94, v95 offset1:1
	ds_write2_b32 v39, v96, v97 offset1:1
	s_waitcnt vmcnt(3)
	ds_write2_b32 v40, v98, v99 offset1:1
	ds_write2_b32 v41, v100, v101 offset1:1
	s_waitcnt vmcnt(2)
	ds_write2_b32 v42, v102, v103 offset1:1
	ds_write2_b32 v43, v104, v105 offset1:1
	s_waitcnt vmcnt(1)
	ds_write2_b32 v44, v106, v107 offset1:1
	ds_write2_b32 v45, v108, v109 offset1:1
	s_waitcnt vmcnt(0)
	ds_write2_b32 v46, v110, v111 offset1:1
	ds_write2_b32 v47, v112, v113 offset1:1
	s_waitcnt lgkmcnt(0)
	ds_read2_b32 v[54:55], v9 offset0:33 offset1:37
	ds_read2_b32 v[56:57], v9 offset1:4
	ds_read2_b32 v[58:59], v9 offset0:66 offset1:70
	ds_read2_b32 v[60:61], v9 offset0:99 offset1:103
	ds_read2_b32 v[62:63], v9 offset0:132 offset1:136
	ds_read2_b32 v[64:65], v9 offset0:165 offset1:169
	ds_read2_b32 v[66:67], v9 offset0:198 offset1:202
	ds_read2_b32 v[68:69], v9 offset0:231 offset1:235
	v_lshl_add_u64 v[50:51], s[16:17], 0, v[4:5]
	v_or_b32_e32 v5, s8, v8
	v_lshl_add_u64 v[70:71], v[50:51], 0, s[10:11]
	v_lshlrev_b32_e32 v72, 12, v5
	v_mov_b32_e32 v73, v3
	s_waitcnt lgkmcnt(6)
	v_cvt_pk_bf16_f32 v50, v56, v54
	s_waitcnt lgkmcnt(4)
	v_cvt_pk_bf16_f32 v51, v58, v60
	s_waitcnt lgkmcnt(2)
	v_cvt_pk_bf16_f32 v52, v62, v64
	s_waitcnt lgkmcnt(0)
; #define LAS __attribute__((address_space(3)))
; DI unsigned pk2(float a, float b) { f32x2 v = {a, b}; bf16v2 r = __builtin_convertvector(v, bf16v2); return __builtin_bit_cast(unsigned, r); }
; DI void p0_transpose_item(const float* W, int K, int N, bf16_t* WT, LAS float* scr, int item, int lane) {
;     ...
;     for (int i = 0; i < 16; ++i) v[i] = *(const f32x4*)(W + (size_t)(k0 + kr + 8 * i) * N + n0 + 4 * n4);
; #pragma unroll
;     for (int i = 0; i < 16; ++i) { LAS float* d = scr + (kr + 8 * i) * 33 + 4 * n4; d[0] = v[i][0]; d[1] = v[i][1]; d[2] = v[i][2]; d[3] = v[i][3]; }
;     asm volatile("s_waitcnt lgkmcnt(0)" ::: "memory");
;     const int c = lane & 15;
; #pragma unroll
;     for (int j = 0; j < 8; ++j) { const int n = (lane >> 4) + 4 * j; const LAS float* s = scr + (8 * c) * 33 + n;
;         u32x4 o; o.x = pk2(s[0 * 33], s[1 * 33]); o.y = pk2(s[2 * 33], s[3 * 33]); o.z = pk2(s[4 * 33], s[5 * 33]); o.w = pk2(s[6 * 33], s[7 * 33]);
;         *(u32x4*)(WT + (size_t)(n0 + n) * K + k0 + 8 * c) = o; }
	v_cvt_pk_bf16_f32 v53, v66, v68
	v_lshl_add_u64 v[72:73], v[70:71], 0, v[72:73]
	global_store_dwordx4 v[72:73], v[50:53], off nt
	v_or_b32_e32 v5, s8, v10
	v_lshlrev_b32_e32 v54, 12, v5
	v_cvt_pk_bf16_f32 v50, v57, v55
	v_cvt_pk_bf16_f32 v51, v59, v61
	v_cvt_pk_bf16_f32 v52, v63, v65
	v_cvt_pk_bf16_f32 v53, v67, v69
	ds_read2_b32 v[56:57], v9 offset0:41 offset1:45
	ds_read2_b32 v[58:59], v9 offset0:8 offset1:12
	ds_read2_b32 v[60:61], v9 offset0:74 offset1:78
	ds_read2_b32 v[62:63], v9 offset0:107 offset1:111
	ds_read2_b32 v[64:65], v9 offset0:140 offset1:144
	ds_read2_b32 v[66:67], v9 offset0:173 offset1:177
	ds_read2_b32 v[68:69], v9 offset0:206 offset1:210
	ds_read2_b32 v[72:73], v9 offset0:239 offset1:243
	v_mov_b32_e32 v55, v3
	v_lshl_add_u64 v[54:55], v[70:71], 0, v[54:55]
	v_or_b32_e32 v5, s8, v11
	global_store_dwordx4 v[54:55], v[50:53], off nt
	v_lshlrev_b32_e32 v54, 12, v5
	v_mov_b32_e32 v55, v3
	s_waitcnt lgkmcnt(6)
	v_cvt_pk_bf16_f32 v50, v58, v56
	s_waitcnt lgkmcnt(4)
	v_cvt_pk_bf16_f32 v51, v60, v62
	s_waitcnt lgkmcnt(2)
	v_cvt_pk_bf16_f32 v52, v64, v66
	s_waitcnt lgkmcnt(0)
	v_cvt_pk_bf16_f32 v53, v68, v72
	v_lshl_add_u64 v[54:55], v[70:71], 0, v[54:55]
	global_store_dwordx4 v[54:55], v[50:53], off nt
	v_or_b32_e32 v5, s8, v12
	v_lshlrev_b32_e32 v54, 12, v5
	v_cvt_pk_bf16_f32 v50, v59, v57
	v_cvt_pk_bf16_f32 v51, v61, v63
	v_cvt_pk_bf16_f32 v52, v65, v67
	v_cvt_pk_bf16_f32 v53, v69, v73
	ds_read2_b32 v[56:57], v9 offset0:16 offset1:20
	ds_read2_b32 v[58:59], v9 offset0:49 offset1:53
	ds_read2_b32 v[60:61], v9 offset0:82 offset1:86
	ds_read2_b32 v[62:63], v9 offset0:115 offset1:119
	ds_read2_b32 v[64:65], v9 offset0:148 offset1:152
	ds_read2_b32 v[66:67], v9 offset0:181 offset1:185
	ds_read2_b32 v[68:69], v9 offset0:214 offset1:218
	ds_read2_b32 v[72:73], v9 offset0:247 offset1:251
	v_mov_b32_e32 v55, v3
	v_lshl_add_u64 v[54:55], v[70:71], 0, v[54:55]
	v_or_b32_e32 v5, s8, v13
	global_store_dwordx4 v[54:55], v[50:53], off nt
	v_lshlrev_b32_e32 v54, 12, v5
	v_mov_b32_e32 v55, v3
	s_waitcnt lgkmcnt(6)
	v_cvt_pk_bf16_f32 v50, v56, v58
	s_waitcnt lgkmcnt(4)
	v_cvt_pk_bf16_f32 v51, v60, v62
	s_waitcnt lgkmcnt(2)
	v_cvt_pk_bf16_f32 v52, v64, v66
	s_waitcnt lgkmcnt(0)
	v_cvt_pk_bf16_f32 v53, v68, v72
	v_lshl_add_u64 v[54:55], v[70:71], 0, v[54:55]
	global_store_dwordx4 v[54:55], v[50:53], off nt
	v_or_b32_e32 v5, s8, v14
	v_lshlrev_b32_e32 v54, 12, v5
	v_cvt_pk_bf16_f32 v50, v57, v59
	v_cvt_pk_bf16_f32 v51, v61, v63
	v_cvt_pk_bf16_f32 v52, v65, v67
	v_cvt_pk_bf16_f32 v53, v69, v73
	ds_read2_b32 v[56:57], v9 offset0:24 offset1:28
	ds_read2_b32 v[58:59], v9 offset0:57 offset1:61
	ds_read2_b32 v[60:61], v9 offset0:90 offset1:94
	ds_read2_b32 v[62:63], v9 offset0:123 offset1:127
	ds_read2_b32 v[64:65], v9 offset0:156 offset1:160
	ds_read2_b32 v[66:67], v9 offset0:189 offset1:193
	ds_read2_b32 v[68:69], v9 offset0:222 offset1:226
	ds_read2_b32 v[72:73], v48 offset0:127 offset1:131
	v_mov_b32_e32 v55, v3
	v_lshl_add_u64 v[54:55], v[70:71], 0, v[54:55]
	v_or_b32_e32 v5, s8, v15
	global_store_dwordx4 v[54:55], v[50:53], off nt
	v_lshlrev_b32_e32 v54, 12, v5
	v_mov_b32_e32 v55, v3
	s_waitcnt lgkmcnt(6)
	v_cvt_pk_bf16_f32 v50, v56, v58
	s_waitcnt lgkmcnt(4)
	v_cvt_pk_bf16_f32 v51, v60, v62
	s_waitcnt lgkmcnt(2)
	v_cvt_pk_bf16_f32 v52, v64, v66
	s_waitcnt lgkmcnt(0)
	v_cvt_pk_bf16_f32 v53, v68, v72
	v_lshl_add_u64 v[54:55], v[70:71], 0, v[54:55]
	v_or_b32_e32 v5, s8, v16
	global_store_dwordx4 v[54:55], v[50:53], off nt
	v_lshlrev_b32_e32 v54, 12, v5
	v_mov_b32_e32 v55, v3
	v_cvt_pk_bf16_f32 v50, v57, v59
	v_cvt_pk_bf16_f32 v51, v61, v63
	v_cvt_pk_bf16_f32 v52, v65, v67
	v_cvt_pk_bf16_f32 v53, v69, v73
	v_lshl_add_u64 v[54:55], v[70:71], 0, v[54:55]
	global_store_dwordx4 v[54:55], v[50:53], off nt
	s_waitcnt lgkmcnt(0)
	s_mov_b64 s[16:17], 0
.LBB0_21:
	s_andn2_b64 vcc, exec, s[16:17]
	s_cbranch_vccnz .LBB0_23
	s_add_i32 s18, s64, 0xffffe600
	s_lshr_b32 s8, s18, 12
	s_lshl_b64 s[16:17], s[8:9], 26
	s_waitcnt lgkmcnt(0)
	s_add_u32 s16, s84, s16
	s_addc_u32 s17, s85, s17
	s_mul_hi_u32 s19, s8, 0x4200000
	s_mul_i32 s8, s8, 0x4200000
	s_add_u32 s65, s94, s8
	s_addc_u32 s19, s95, s19
	s_lshr_b32 s8, s18, 1
	s_and_b32 s18, s8, 0x780
	s_and_b32 s8, s20, 0x1fe0
	s_lshl_b32 s66, s8, 2
	s_add_u32 s16, s16, s66
	v_or_b32_e32 v5, s18, v6
	s_addc_u32 s17, s17, 0
	v_lshl_add_u64 v[50:51], s[16:17], 0, v[2:3]
	v_lshlrev_b32_e32 v52, 15, v5
	v_mov_b32_e32 v53, v3
	v_lshl_add_u64 v[110:111], v[50:51], 0, v[52:53]
	v_add_co_u32_e32 v54, vcc, s25, v110
	s_lshl_b32 s16, s18, 1
	s_nop 0
	v_addc_co_u32_e32 v55, vcc, 0, v111, vcc
	v_add_co_u32_e32 v58, vcc, s29, v110
	global_load_dwordx4 v[50:53], v[110:111], off nt
	s_nop 0
	global_load_dwordx4 v[54:57], v[54:55], off nt
	v_addc_co_u32_e32 v59, vcc, 0, v111, vcc
	v_add_co_u32_e32 v62, vcc, s34, v110
	s_add_u32 s16, s65, s16
	s_nop 0
	v_addc_co_u32_e32 v63, vcc, 0, v111, vcc
	v_add_co_u32_e32 v66, vcc, s38, v110
	global_load_dwordx4 v[58:61], v[58:59], off nt
	s_nop 0
	global_load_dwordx4 v[62:65], v[62:63], off nt
	v_addc_co_u32_e32 v67, vcc, 0, v111, vcc
	v_add_co_u32_e32 v70, vcc, s39, v110
	s_addc_u32 s17, s19, 0
	s_nop 0
	v_addc_co_u32_e32 v71, vcc, 0, v111, vcc
	v_add_co_u32_e32 v74, vcc, s40, v110
	global_load_dwordx4 v[66:69], v[66:67], off nt
	s_nop 0
	global_load_dwordx4 v[70:73], v[70:71], off nt
	v_addc_co_u32_e32 v75, vcc, 0, v111, vcc
	v_add_co_u32_e32 v78, vcc, s41, v110
	v_mov_b32_e32 v5, v3
	s_nop 0
	v_addc_co_u32_e32 v79, vcc, 0, v111, vcc
	v_add_co_u32_e32 v82, vcc, s42, v110
	global_load_dwordx4 v[74:77], v[74:75], off nt
	s_nop 0
	global_load_dwordx4 v[78:81], v[78:79], off nt
	v_addc_co_u32_e32 v83, vcc, 0, v111, vcc
	v_add_co_u32_e32 v86, vcc, s43, v110
	s_nop 1
	v_addc_co_u32_e32 v87, vcc, 0, v111, vcc
	v_add_co_u32_e32 v90, vcc, s44, v110
	global_load_dwordx4 v[82:85], v[82:83], off nt
	s_nop 0
	global_load_dwordx4 v[86:89], v[86:87], off nt
	v_addc_co_u32_e32 v91, vcc, 0, v111, vcc
	v_add_co_u32_e32 v94, vcc, s45, v110
	s_nop 1
	v_addc_co_u32_e32 v95, vcc, 0, v111, vcc
	v_add_co_u32_e32 v98, vcc, s46, v110
	global_load_dwordx4 v[90:93], v[90:91], off nt
	s_nop 0
	global_load_dwordx4 v[94:97], v[94:95], off nt
	v_addc_co_u32_e32 v99, vcc, 0, v111, vcc
	v_add_co_u32_e32 v102, vcc, s47, v110
	s_nop 1
	v_addc_co_u32_e32 v103, vcc, 0, v111, vcc
	global_load_dwordx4 v[98:101], v[98:99], off nt
	s_nop 0
	global_load_dwordx4 v[102:105], v[102:103], off nt
	v_add_co_u32_e32 v106, vcc, s48, v110
	s_nop 1
	v_addc_co_u32_e32 v107, vcc, 0, v111, vcc
	global_load_dwordx4 v[106:109], v[106:107], off nt
	v_add_co_u32_e32 v110, vcc, s49, v110
	s_nop 1
	v_addc_co_u32_e32 v111, vcc, 0, v111, vcc
	global_load_dwordx4 v[110:113], v[110:111], off nt
	s_waitcnt vmcnt(15)
; #define LAS __attribute__((address_space(3)))
; DI unsigned pk2(float a, float b) { f32x2 v = {a, b}; bf16v2 r = __builtin_convertvector(v, bf16v2); return __builtin_bit_cast(unsigned, r); }
; DI void p0_transpose_item(const float* W, int K, int N, bf16_t* WT, LAS float* scr, int item, int lane) {
;     ...
;     for (int i = 0; i < 16; ++i) { LAS float* d = scr + (kr + 8 * i) * 33 + 4 * n4; d[0] = v[i][0]; d[1] = v[i][1]; d[2] = v[i][2]; d[3] = v[i][3]; }
;     asm volatile("s_waitcnt lgkmcnt(0)" ::: "memory");
;     const int c = lane & 15;
; #pragma unroll
;     for (int j = 0; j < 8; ++j) { const int n = (lane >> 4) + 4 * j; const LAS float* s = scr + (8 * c) * 33 + n;
;         u32x4 o; o.x = pk2(s[0 * 33], s[1 * 33]); o.y = pk2(s[2 * 33], s[3 * 33]); o.z = pk2(s[4 * 33], s[5 * 33]); o.w = pk2(s[6 * 33], s[7 * 33]);
;         *(u32x4*)(WT + (size_t)(n0 + n) * K + k0 + 8 * c) = o; }
;     asm volatile("s_waitcnt lgkmcnt(0)" ::: "memory");
	ds_write2_b32 v7, v50, v51 offset1:1
	ds_write2_b32 v7, v52, v53 offset0:2 offset1:3
	s_waitcnt vmcnt(14)
	ds_write2_b32 v17, v54, v55 offset1:1
	ds_write2_b32 v18, v56, v57 offset1:1
	s_waitcnt vmcnt(13)
	ds_write2_b32 v19, v58, v59 offset1:1
	ds_write2_b32 v20, v60, v61 offset1:1
	s_waitcnt vmcnt(12)
	ds_write2_b32 v21, v62, v63 offset1:1
	ds_write2_b32 v22, v64, v65 offset1:1
	s_waitcnt vmcnt(11)
	ds_write2_b32 v23, v66, v67 offset1:1
	ds_write2_b32 v24, v68, v69 offset1:1
	s_waitcnt vmcnt(10)
	ds_write2_b32 v25, v70, v71 offset1:1
	ds_write2_b32 v26, v72, v73 offset1:1
	s_waitcnt vmcnt(9)
	ds_write2_b32 v27, v74, v75 offset1:1
	ds_write2_b32 v28, v76, v77 offset1:1
	s_waitcnt vmcnt(8)
	ds_write2_b32 v29, v78, v79 offset1:1
	ds_write2_b32 v30, v80, v81 offset1:1
	s_waitcnt vmcnt(7)
	ds_write2_b32 v31, v82, v83 offset1:1
	ds_write2_b32 v32, v84, v85 offset1:1
	s_waitcnt vmcnt(6)
	ds_write2_b32 v33, v86, v87 offset1:1
	ds_write2_b32 v35, v88, v89 offset1:1
	s_waitcnt vmcnt(5)
	ds_write2_b32 v36, v90, v91 offset1:1
	ds_write2_b32 v37, v92, v93 offset1:1
	s_waitcnt vmcnt(4)
	ds_write2_b32 v38, v94, v95 offset1:1
	ds_write2_b32 v39, v96, v97 offset1:1
	s_waitcnt vmcnt(3)
	ds_write2_b32 v40, v98, v99 offset1:1
	ds_write2_b32 v41, v100, v101 offset1:1
	s_waitcnt vmcnt(2)
	ds_write2_b32 v42, v102, v103 offset1:1
	ds_write2_b32 v43, v104, v105 offset1:1
	s_waitcnt vmcnt(1)
	ds_write2_b32 v44, v106, v107 offset1:1
	ds_write2_b32 v45, v108, v109 offset1:1
	s_waitcnt vmcnt(0)
	ds_write2_b32 v46, v110, v111 offset1:1
	ds_write2_b32 v47, v112, v113 offset1:1
	s_waitcnt lgkmcnt(0)
	ds_read2_b32 v[54:55], v9 offset0:33 offset1:37
	ds_read2_b32 v[56:57], v9 offset1:4
	ds_read2_b32 v[58:59], v9 offset0:66 offset1:70
	ds_read2_b32 v[60:61], v9 offset0:99 offset1:103
	ds_read2_b32 v[62:63], v9 offset0:132 offset1:136
	ds_read2_b32 v[64:65], v9 offset0:165 offset1:169
	ds_read2_b32 v[66:67], v9 offset0:198 offset1:202
	ds_read2_b32 v[68:69], v9 offset0:231 offset1:235
	v_lshl_add_u64 v[50:51], s[16:17], 0, v[4:5]
	v_or_b32_e32 v5, s8, v8
	v_lshl_add_u64 v[70:71], v[50:51], 0, s[12:13]
	v_lshlrev_b32_e32 v72, 12, v5
	v_mov_b32_e32 v73, v3
	s_waitcnt lgkmcnt(6)
	v_cvt_pk_bf16_f32 v50, v56, v54
	s_waitcnt lgkmcnt(4)
	v_cvt_pk_bf16_f32 v51, v58, v60
	s_waitcnt lgkmcnt(2)
	v_cvt_pk_bf16_f32 v52, v62, v64
	s_waitcnt lgkmcnt(0)
	v_cvt_pk_bf16_f32 v53, v66, v68
	v_lshl_add_u64 v[72:73], v[70:71], 0, v[72:73]
	global_store_dwordx4 v[72:73], v[50:53], off nt
	v_or_b32_e32 v5, s8, v10
	v_lshlrev_b32_e32 v54, 12, v5
	v_cvt_pk_bf16_f32 v50, v57, v55
	v_cvt_pk_bf16_f32 v51, v59, v61
	v_cvt_pk_bf16_f32 v52, v63, v65
	v_cvt_pk_bf16_f32 v53, v67, v69
	ds_read2_b32 v[56:57], v9 offset0:41 offset1:45
	ds_read2_b32 v[58:59], v9 offset0:8 offset1:12
	ds_read2_b32 v[60:61], v9 offset0:74 offset1:78
	ds_read2_b32 v[62:63], v9 offset0:107 offset1:111
	ds_read2_b32 v[64:65], v9 offset0:140 offset1:144
	ds_read2_b32 v[66:67], v9 offset0:173 offset1:177
	ds_read2_b32 v[68:69], v9 offset0:206 offset1:210
	ds_read2_b32 v[72:73], v9 offset0:239 offset1:243
	v_mov_b32_e32 v55, v3
	v_lshl_add_u64 v[54:55], v[70:71], 0, v[54:55]
	v_or_b32_e32 v5, s8, v11
	global_store_dwordx4 v[54:55], v[50:53], off nt
	v_lshlrev_b32_e32 v54, 12, v5
	v_mov_b32_e32 v55, v3
	s_waitcnt lgkmcnt(6)
	v_cvt_pk_bf16_f32 v50, v58, v56
	s_waitcnt lgkmcnt(4)
	v_cvt_pk_bf16_f32 v51, v60, v62
	s_waitcnt lgkmcnt(2)
	v_cvt_pk_bf16_f32 v52, v64, v66
	s_waitcnt lgkmcnt(0)
	v_cvt_pk_bf16_f32 v53, v68, v72
	v_lshl_add_u64 v[54:55], v[70:71], 0, v[54:55]
	global_store_dwordx4 v[54:55], v[50:53], off nt
	v_or_b32_e32 v5, s8, v12
	v_lshlrev_b32_e32 v54, 12, v5
	v_cvt_pk_bf16_f32 v50, v59, v57
	v_cvt_pk_bf16_f32 v51, v61, v63
	v_cvt_pk_bf16_f32 v52, v65, v67
	v_cvt_pk_bf16_f32 v53, v69, v73
	ds_read2_b32 v[56:57], v9 offset0:16 offset1:20
	ds_read2_b32 v[58:59], v9 offset0:49 offset1:53
	ds_read2_b32 v[60:61], v9 offset0:82 offset1:86
	ds_read2_b32 v[62:63], v9 offset0:115 offset1:119
	ds_read2_b32 v[64:65], v9 offset0:148 offset1:152
	ds_read2_b32 v[66:67], v9 offset0:181 offset1:185
	ds_read2_b32 v[68:69], v9 offset0:214 offset1:218
	ds_read2_b32 v[72:73], v9 offset0:247 offset1:251
	v_mov_b32_e32 v55, v3
	v_lshl_add_u64 v[54:55], v[70:71], 0, v[54:55]
	v_or_b32_e32 v5, s8, v13
	global_store_dwordx4 v[54:55], v[50:53], off nt
	v_lshlrev_b32_e32 v54, 12, v5
	v_mov_b32_e32 v55, v3
	s_waitcnt lgkmcnt(6)
	v_cvt_pk_bf16_f32 v50, v56, v58
	s_waitcnt lgkmcnt(4)
	v_cvt_pk_bf16_f32 v51, v60, v62
	s_waitcnt lgkmcnt(2)
	v_cvt_pk_bf16_f32 v52, v64, v66
	s_waitcnt lgkmcnt(0)
	v_cvt_pk_bf16_f32 v53, v68, v72
	v_lshl_add_u64 v[54:55], v[70:71], 0, v[54:55]
	global_store_dwordx4 v[54:55], v[50:53], off nt
	v_or_b32_e32 v5, s8, v14
	v_lshlrev_b32_e32 v54, 12, v5
	v_cvt_pk_bf16_f32 v50, v57, v59
	v_cvt_pk_bf16_f32 v51, v61, v63
	v_cvt_pk_bf16_f32 v52, v65, v67
	v_cvt_pk_bf16_f32 v53, v69, v73
	ds_read2_b32 v[56:57], v9 offset0:24 offset1:28
	ds_read2_b32 v[58:59], v9 offset0:57 offset1:61
	ds_read2_b32 v[60:61], v9 offset0:90 offset1:94
	ds_read2_b32 v[62:63], v9 offset0:123 offset1:127
	ds_read2_b32 v[64:65], v9 offset0:156 offset1:160
	ds_read2_b32 v[66:67], v9 offset0:189 offset1:193
	ds_read2_b32 v[68:69], v9 offset0:222 offset1:226
	ds_read2_b32 v[72:73], v48 offset0:127 offset1:131
	v_mov_b32_e32 v55, v3
	v_lshl_add_u64 v[54:55], v[70:71], 0, v[54:55]
	v_or_b32_e32 v5, s8, v15
	global_store_dwordx4 v[54:55], v[50:53], off nt
	v_lshlrev_b32_e32 v54, 12, v5
	v_mov_b32_e32 v55, v3
	s_waitcnt lgkmcnt(6)
	v_cvt_pk_bf16_f32 v50, v56, v58
	s_waitcnt lgkmcnt(4)
	v_cvt_pk_bf16_f32 v51, v60, v62
	s_waitcnt lgkmcnt(2)
	v_cvt_pk_bf16_f32 v52, v64, v66
	s_waitcnt lgkmcnt(0)
	v_cvt_pk_bf16_f32 v53, v68, v72
	v_lshl_add_u64 v[54:55], v[70:71], 0, v[54:55]
	v_or_b32_e32 v5, s8, v16
	global_store_dwordx4 v[54:55], v[50:53], off nt
	v_lshlrev_b32_e32 v54, 12, v5
	v_mov_b32_e32 v55, v3
	v_cvt_pk_bf16_f32 v50, v57, v59
	v_cvt_pk_bf16_f32 v51, v61, v63
	v_cvt_pk_bf16_f32 v52, v65, v67
	v_cvt_pk_bf16_f32 v53, v69, v73
	v_lshl_add_u64 v[54:55], v[70:71], 0, v[54:55]
	global_store_dwordx4 v[54:55], v[50:53], off nt
	s_waitcnt lgkmcnt(0)

; #define LAS __attribute__((address_space(3)))
; DI void p0_transpose_item(const float* W, int K, int N, bf16_t* WT, LAS float* scr, int item, int lane) {
;     ...
;     for (int i = 0; i < 16; ++i) v[i] = *(const f32x4*)(W + (size_t)(k0 + kr + 8 * i) * N + n0 + 4 * n4);
; #pragma unroll
;     for (int i = 0; i < 16; ++i) { LAS float* d = scr + (kr + 8 * i) * 33 + 4 * n4; d[0] = v[i][0]; d[1] = v[i][1]; d[2] = v[i][2]; d[3] = v[i][3]; }
; DI void phase_p0(const Params& p, LAS unsigned char* lds, int gw, int NGW, int wave, int lane) {
;     ...
;         if (r < 2 * I_OUT) { const int j = r / I_OUT; p0_transpose_item(p.w_out_a + (size_t)j * D * D, D, D, (bf16_t*)(p.ws + WS_W + j * WPAIR + WO_OUTA), scr, r % I_OUT, lane); continue; } r -= 2 * I_OUT;
.LBB0_24:
	s_andn2_b64 vcc, exec, s[16:17]
	s_cbranch_vccnz .LBB0_26
	s_add_i32 s8, s64, 0xffffee00
	s_lshr_b32 s8, s8, 10
	s_lshl_b64 s[16:17], s[8:9], 24
	s_waitcnt lgkmcnt(0)
	s_add_u32 s16, s82, s16
	s_addc_u32 s17, s83, s17
	s_mul_hi_u32 s18, s8, 0x4200000
	s_mul_i32 s8, s8, 0x4200000
	s_add_u32 s19, s94, s8
	s_addc_u32 s18, s95, s18
	s_add_i32 s8, s1, 0x5000
	s_and_b32 s65, s8, 0x780
	s_and_b32 s8, s20, 0x7e0
	s_lshl_b32 s66, s8, 2
	s_add_u32 s16, s16, s66
	v_or_b32_e32 v5, s65, v6
	s_addc_u32 s17, s17, 0
	v_lshl_add_u64 v[50:51], s[16:17], 0, v[2:3]
	v_lshlrev_b32_e32 v52, 13, v5
	v_mov_b32_e32 v53, v3
	v_lshl_add_u64 v[110:111], v[50:51], 0, v[52:53]
	v_add_co_u32_e32 v54, vcc, s22, v110
	s_lshl_b32 s16, s65, 1
	s_nop 0
	v_addc_co_u32_e32 v55, vcc, 0, v111, vcc
	v_add_co_u32_e32 v58, vcc, s23, v110
	global_load_dwordx4 v[50:53], v[110:111], off nt
	s_nop 0
	global_load_dwordx4 v[54:57], v[54:55], off nt
	v_addc_co_u32_e32 v59, vcc, 0, v111, vcc
	v_add_co_u32_e32 v62, vcc, s24, v110
	s_add_u32 s16, s19, s16
	s_nop 0
	v_addc_co_u32_e32 v63, vcc, 0, v111, vcc
	v_add_co_u32_e32 v66, vcc, s25, v110
	global_load_dwordx4 v[58:61], v[58:59], off nt
	s_nop 0
	global_load_dwordx4 v[62:65], v[62:63], off nt
	v_addc_co_u32_e32 v67, vcc, 0, v111, vcc
	v_add_co_u32_e32 v70, vcc, s26, v110
	s_addc_u32 s17, s18, 0
	s_nop 0
	v_addc_co_u32_e32 v71, vcc, 0, v111, vcc
	v_add_co_u32_e32 v74, vcc, s27, v110
	global_load_dwordx4 v[66:69], v[66:67], off nt
	s_nop 0
	global_load_dwordx4 v[70:73], v[70:71], off nt
	v_addc_co_u32_e32 v75, vcc, 0, v111, vcc
	v_add_co_u32_e32 v78, vcc, s28, v110
	v_mov_b32_e32 v5, v3
	s_nop 0
	v_addc_co_u32_e32 v79, vcc, 0, v111, vcc
	v_add_co_u32_e32 v82, vcc, s29, v110
	global_load_dwordx4 v[74:77], v[74:75], off nt
	s_nop 0
	global_load_dwordx4 v[78:81], v[78:79], off nt
	v_addc_co_u32_e32 v83, vcc, 0, v111, vcc
	v_add_co_u32_e32 v86, vcc, s30, v110
	s_nop 1
	v_addc_co_u32_e32 v87, vcc, 0, v111, vcc
	v_add_co_u32_e32 v90, vcc, s31, v110
	global_load_dwordx4 v[82:85], v[82:83], off nt
	s_nop 0
	global_load_dwordx4 v[86:89], v[86:87], off nt
	v_addc_co_u32_e32 v91, vcc, 0, v111, vcc
	v_add_co_u32_e32 v94, vcc, s33, v110
	s_nop 1
	v_addc_co_u32_e32 v95, vcc, 0, v111, vcc
	v_add_co_u32_e32 v98, vcc, s34, v110
	global_load_dwordx4 v[90:93], v[90:91], off nt
	s_nop 0
	global_load_dwordx4 v[94:97], v[94:95], off nt
	v_addc_co_u32_e32 v99, vcc, 0, v111, vcc
	v_add_co_u32_e32 v102, vcc, s35, v110
	s_nop 1
	v_addc_co_u32_e32 v103, vcc, 0, v111, vcc
	global_load_dwordx4 v[98:101], v[98:99], off nt
	s_nop 0
	global_load_dwordx4 v[102:105], v[102:103], off nt
	v_add_co_u32_e32 v106, vcc, s36, v110
	s_nop 1
	v_addc_co_u32_e32 v107, vcc, 0, v111, vcc
	global_load_dwordx4 v[106:109], v[106:107], off nt
	v_add_co_u32_e32 v110, vcc, s37, v110
	s_nop 1
	v_addc_co_u32_e32 v111, vcc, 0, v111, vcc
	global_load_dwordx4 v[110:113], v[110:111], off nt
	s_waitcnt vmcnt(15)
	ds_write2_b32 v7, v50, v51 offset1:1
	ds_write2_b32 v7, v52, v53 offset0:2 offset1:3
	s_waitcnt vmcnt(14)
	ds_write2_b32 v17, v54, v55 offset1:1
	ds_write2_b32 v18, v56, v57 offset1:1
	s_waitcnt vmcnt(13)
	ds_write2_b32 v19, v58, v59 offset1:1
	ds_write2_b32 v20, v60, v61 offset1:1
	s_waitcnt vmcnt(12)
	ds_write2_b32 v21, v62, v63 offset1:1
	ds_write2_b32 v22, v64, v65 offset1:1
	s_waitcnt vmcnt(11)
	ds_write2_b32 v23, v66, v67 offset1:1
	ds_write2_b32 v24, v68, v69 offset1:1
	s_waitcnt vmcnt(10)
	ds_write2_b32 v25, v70, v71 offset1:1
	ds_write2_b32 v26, v72, v73 offset1:1
	s_waitcnt vmcnt(9)
	ds_write2_b32 v27, v74, v75 offset1:1
	ds_write2_b32 v28, v76, v77 offset1:1
	s_waitcnt vmcnt(8)
	ds_write2_b32 v29, v78, v79 offset1:1
	ds_write2_b32 v30, v80, v81 offset1:1
	s_waitcnt vmcnt(7)
	ds_write2_b32 v31, v82, v83 offset1:1
	ds_write2_b32 v32, v84, v85 offset1:1
	s_waitcnt vmcnt(6)
	ds_write2_b32 v33, v86, v87 offset1:1
	ds_write2_b32 v35, v88, v89 offset1:1
	s_waitcnt vmcnt(5)
	ds_write2_b32 v36, v90, v91 offset1:1
	ds_write2_b32 v37, v92, v93 offset1:1
	s_waitcnt vmcnt(4)
	ds_write2_b32 v38, v94, v95 offset1:1
	ds_write2_b32 v39, v96, v97 offset1:1
	s_waitcnt vmcnt(3)
	ds_write2_b32 v40, v98, v99 offset1:1
	ds_write2_b32 v41, v100, v101 offset1:1
	s_waitcnt vmcnt(2)
	ds_write2_b32 v42, v102, v103 offset1:1
	ds_write2_b32 v43, v104, v105 offset1:1
	s_waitcnt vmcnt(1)
	ds_write2_b32 v44, v106, v107 offset1:1
	ds_write2_b32 v45, v108, v109 offset1:1
	s_waitcnt vmcnt(0)
	ds_write2_b32 v46, v110, v111 offset1:1
	ds_write2_b32 v47, v112, v113 offset1:1
	s_waitcnt lgkmcnt(0)
; #define LAS __attribute__((address_space(3)))
; DI unsigned pk2(float a, float b) { f32x2 v = {a, b}; bf16v2 r = __builtin_convertvector(v, bf16v2); return __builtin_bit_cast(unsigned, r); }
; DI void p0_transpose_item(const float* W, int K, int N, bf16_t* WT, LAS float* scr, int item, int lane) {
;     ...
;     const int c = lane & 15;
; #pragma unroll
;     for (int j = 0; j < 8; ++j) { const int n = (lane >> 4) + 4 * j; const LAS float* s = scr + (8 * c) * 33 + n;
;         u32x4 o; o.x = pk2(s[0 * 33], s[1 * 33]); o.y = pk2(s[2 * 33], s[3 * 33]); o.z = pk2(s[4 * 33], s[5 * 33]); o.w = pk2(s[6 * 33], s[7 * 33]);
;         *(u32x4*)(WT + (size_t)(n0 + n) * K + k0 + 8 * c) = o; }
;     asm volatile("s_waitcnt lgkmcnt(0)" ::: "memory");
	ds_read2_b32 v[54:55], v9 offset0:33 offset1:37
	ds_read2_b32 v[56:57], v9 offset1:4
	ds_read2_b32 v[58:59], v9 offset0:66 offset1:70
	ds_read2_b32 v[60:61], v9 offset0:99 offset1:103
	ds_read2_b32 v[62:63], v9 offset0:132 offset1:136
	ds_read2_b32 v[64:65], v9 offset0:165 offset1:169
	ds_read2_b32 v[66:67], v9 offset0:198 offset1:202
	ds_read2_b32 v[68:69], v9 offset0:231 offset1:235
	v_lshl_add_u64 v[50:51], s[16:17], 0, v[4:5]
	v_or_b32_e32 v5, s8, v8
	v_lshl_add_u64 v[70:71], v[50:51], 0, s[14:15]
	v_lshlrev_b32_e32 v72, 12, v5
	v_mov_b32_e32 v73, v3
	s_waitcnt lgkmcnt(6)
	v_cvt_pk_bf16_f32 v50, v56, v54
	s_waitcnt lgkmcnt(4)
	v_cvt_pk_bf16_f32 v51, v58, v60
	s_waitcnt lgkmcnt(2)
	v_cvt_pk_bf16_f32 v52, v62, v64
	s_waitcnt lgkmcnt(0)
	v_cvt_pk_bf16_f32 v53, v66, v68
	v_lshl_add_u64 v[72:73], v[70:71], 0, v[72:73]
	global_store_dwordx4 v[72:73], v[50:53], off nt
	v_or_b32_e32 v5, s8, v10
	v_lshlrev_b32_e32 v54, 12, v5
	v_cvt_pk_bf16_f32 v50, v57, v55
	v_cvt_pk_bf16_f32 v51, v59, v61
	v_cvt_pk_bf16_f32 v52, v63, v65
	v_cvt_pk_bf16_f32 v53, v67, v69
	ds_read2_b32 v[56:57], v9 offset0:41 offset1:45
	ds_read2_b32 v[58:59], v9 offset0:8 offset1:12
	ds_read2_b32 v[60:61], v9 offset0:74 offset1:78
	ds_read2_b32 v[62:63], v9 offset0:107 offset1:111
	ds_read2_b32 v[64:65], v9 offset0:140 offset1:144
	ds_read2_b32 v[66:67], v9 offset0:173 offset1:177
	ds_read2_b32 v[68:69], v9 offset0:206 offset1:210
	ds_read2_b32 v[72:73], v9 offset0:239 offset1:243
	v_mov_b32_e32 v55, v3
	v_lshl_add_u64 v[54:55], v[70:71], 0, v[54:55]
	v_or_b32_e32 v5, s8, v11
	global_store_dwordx4 v[54:55], v[50:53], off nt
	v_lshlrev_b32_e32 v54, 12, v5
	v_mov_b32_e32 v55, v3
	s_waitcnt lgkmcnt(6)
	v_cvt_pk_bf16_f32 v50, v58, v56
	s_waitcnt lgkmcnt(4)
	v_cvt_pk_bf16_f32 v51, v60, v62
	s_waitcnt lgkmcnt(2)
	v_cvt_pk_bf16_f32 v52, v64, v66
	s_waitcnt lgkmcnt(0)
	v_cvt_pk_bf16_f32 v53, v68, v72
	v_lshl_add_u64 v[54:55], v[70:71], 0, v[54:55]
	global_store_dwordx4 v[54:55], v[50:53], off nt
	v_or_b32_e32 v5, s8, v12
	v_lshlrev_b32_e32 v54, 12, v5
	v_cvt_pk_bf16_f32 v50, v59, v57
	v_cvt_pk_bf16_f32 v51, v61, v63
	v_cvt_pk_bf16_f32 v52, v65, v67
	v_cvt_pk_bf16_f32 v53, v69, v73
	ds_read2_b32 v[56:57], v9 offset0:16 offset1:20
	ds_read2_b32 v[58:59], v9 offset0:49 offset1:53
	ds_read2_b32 v[60:61], v9 offset0:82 offset1:86
	ds_read2_b32 v[62:63], v9 offset0:115 offset1:119
	ds_read2_b32 v[64:65], v9 offset0:148 offset1:152
	ds_read2_b32 v[66:67], v9 offset0:181 offset1:185
	ds_read2_b32 v[68:69], v9 offset0:214 offset1:218
	ds_read2_b32 v[72:73], v9 offset0:247 offset1:251
	v_mov_b32_e32 v55, v3
	v_lshl_add_u64 v[54:55], v[70:71], 0, v[54:55]
	v_or_b32_e32 v5, s8, v13
	global_store_dwordx4 v[54:55], v[50:53], off nt
	v_lshlrev_b32_e32 v54, 12, v5
	v_mov_b32_e32 v55, v3
	s_waitcnt lgkmcnt(6)
	v_cvt_pk_bf16_f32 v50, v56, v58
	s_waitcnt lgkmcnt(4)
	v_cvt_pk_bf16_f32 v51, v60, v62
	s_waitcnt lgkmcnt(2)
	v_cvt_pk_bf16_f32 v52, v64, v66
	s_waitcnt lgkmcnt(0)
	v_cvt_pk_bf16_f32 v53, v68, v72
	v_lshl_add_u64 v[54:55], v[70:71], 0, v[54:55]
	global_store_dwordx4 v[54:55], v[50:53], off nt
	v_or_b32_e32 v5, s8, v14
	v_lshlrev_b32_e32 v54, 12, v5
	v_cvt_pk_bf16_f32 v50, v57, v59
	v_cvt_pk_bf16_f32 v51, v61, v63
	v_cvt_pk_bf16_f32 v52, v65, v67
	v_cvt_pk_bf16_f32 v53, v69, v73
	ds_read2_b32 v[56:57], v9 offset0:24 offset1:28
	ds_read2_b32 v[58:59], v9 offset0:57 offset1:61
	ds_read2_b32 v[60:61], v9 offset0:90 offset1:94
	ds_read2_b32 v[62:63], v9 offset0:123 offset1:127
	ds_read2_b32 v[64:65], v9 offset0:156 offset1:160
	ds_read2_b32 v[66:67], v9 offset0:189 offset1:193
	ds_read2_b32 v[68:69], v9 offset0:222 offset1:226
	ds_read2_b32 v[72:73], v48 offset0:127 offset1:131
	v_mov_b32_e32 v55, v3
	v_lshl_add_u64 v[54:55], v[70:71], 0, v[54:55]
	v_or_b32_e32 v5, s8, v15
	global_store_dwordx4 v[54:55], v[50:53], off nt
	v_lshlrev_b32_e32 v54, 12, v5
	v_mov_b32_e32 v55, v3
	s_waitcnt lgkmcnt(6)
	v_cvt_pk_bf16_f32 v50, v56, v58
	s_waitcnt lgkmcnt(4)
	v_cvt_pk_bf16_f32 v51, v60, v62
	s_waitcnt lgkmcnt(2)
	v_cvt_pk_bf16_f32 v52, v64, v66
	s_waitcnt lgkmcnt(0)
	v_cvt_pk_bf16_f32 v53, v68, v72
	v_lshl_add_u64 v[54:55], v[70:71], 0, v[54:55]
	v_or_b32_e32 v5, s8, v16
	global_store_dwordx4 v[54:55], v[50:53], off nt
	v_lshlrev_b32_e32 v54, 12, v5
	v_mov_b32_e32 v55, v3
	v_cvt_pk_bf16_f32 v50, v57, v59
	v_cvt_pk_bf16_f32 v51, v61, v63
	v_cvt_pk_bf16_f32 v52, v65, v67
	v_cvt_pk_bf16_f32 v53, v69, v73
	v_lshl_add_u64 v[54:55], v[70:71], 0, v[54:55]
	global_store_dwordx4 v[54:55], v[50:53], off nt
	s_waitcnt lgkmcnt(0)
